# attention step tail: the 4 cvt_pk writing v180-v183 moved into the lgkmcnt stall slot right after the last MFMA that reads v[180:183] (MFMA-shadow fill, on top of v60)
# baseline (speedup 1.0000x reference)
; #define ATT_WAIT_BAR() asm volatile("s_waitcnt vmcnt(0) lgkmcnt(0)\n\ts_barrier" ::: "memory")
; #define ATT_SB() __builtin_amdgcn_sched_barrier(0)
; #define A16_VLD(v, g) do { const LAS unsigned char* a_ = vbp[(g) & 3] + vso + ((g) >> 4) * 16384 + (((g) & 15) >> 2) * 1024; v[0] = vtr(a_); v[1] = vtr(a_ + 8192); } while (0)
; #define A16_GAP(i) do { A16_EL(i) = __builtin_amdgcn_exp2f(A16_EL(i)); \
;                 if ((i) > 0) { if ((((i) - 1) >> 2) & 1) s1 += A16_EL((i) - 1); else s0 += A16_EL((i) - 1); } asm volatile("" : "+v"(s0), "+v"(s1)); } while (0)
; __device__ __forceinline__ void attn_core16(f32x4 (&O)[16][2], float (&lq)[2], const bf16_t* Qw, int q_pitch, const bf16_t* Kh, const bf16_t* Vh, int kv_pitch,
;                                             int NT, int nt_act, int kch0, float negb, LAS unsigned char* ring, int wid) {
;     ...
;         ATT_WAIT_BAR();
;         if (t < nt_act) {
;             const bool more = (t + 1 < nt_act);
;             const int vso = (t & 1) * SLOTB;
;             s16x4 vv[3][2];
;     ...
;             A16_VLD(vv[0], 0);
;             ATT_SB();
;             A16_QK(t + 1, 1, t);
;             ATT_SB();
;             A16_VLD(vv[1], 1);
;             float s0 = 0.f, s1 = 0.f;
;     ...
; #pragma unroll
;             for (int g = 0; g < 32; ++g) {
;                 if (g + 2 < 32) A16_VLD(vv[(g + 2) % 3], g + 2);
;                 ATT_SB();
;                 O[g & 15][0] = __builtin_amdgcn_mfma_f32_16x16x32_bf16(A16_VF(vv[g % 3]), __builtin_bit_cast(bf16x8, pw[g >> 4][0]), O[g & 15][0], 0, 0, 0);
;                 O[g & 15][1] = __builtin_amdgcn_mfma_f32_16x16x32_bf16(A16_VF(vv[g % 3]), __builtin_bit_cast(bf16x8, pw[g >> 4][1]), O[g & 15][1], 0, 0, 0);
;                 A16_GAP(g);
;                 ATT_SB();
;             }
.LBB0_685:
	s_waitcnt vmcnt(0) lgkmcnt(0)
	s_barrier
	s_add_i32 s20, s0, 1
	s_cmp_ge_u32 s0, s73
	s_cbranch_scc1 .LBB0_687
	s_and_b32 s80, s72, 0x10000
	v_add_u32_e32 v2, s80, v214
	ds_read_b128 v[188:191], v2
	ds_read_b128 v[192:195], v2 offset:8192
	s_add_i32 s48, s72, 0xffff0000
	s_and_b32 s50, s48, 0x10000
	v_add_u32_e32 v0, s50, v216
	ds_read_b64_tr_b16 v[220:221], v0 offset:32768
	ds_read_b64_tr_b16 v[222:223], v0 offset:40960
	s_add_i32 s0, s0, 2
	s_min_u32 vcc_lo, s0, s21
	s_min_u32 s0, s20, s21
	s_lshl_b64 s[70:71], s[0:1], 18
	s_add_u32 s70, s38, s70
	s_mov_b32 vcc_hi, s1
	ds_read_b128 v[200:203], v2 offset:16384
	s_addc_u32 s71, s39, s71
	s_add_i32 s0, s12, s80
	s_lshl_b64 vcc, vcc, 18
	s_add_u32 s54, s18, vcc_lo
	s_addc_u32 s55, s19, vcc_hi
	s_add_i32 vcc_lo, s13, s50
	s_waitcnt lgkmcnt(4)
	v_mfma_f32_16x16x32_bf16 v[196:199], v[188:191], v[136:139], v[168:171]
	s_mov_b32 m0, vcc_lo
	s_nop 0
	global_load_lds_dwordx4 v212, s[54:55]
	v_mfma_f32_16x16x32_bf16 v[188:191], v[188:191], v[152:155], v[168:171]
	ds_read_b128 v[204:207], v2 offset:24576
	s_add_u32 s48, s54, 0x80
	s_waitcnt lgkmcnt(2)
	v_mfma_f32_16x16x32_bf16 v[224:227], v[192:195], v[136:139], v[168:171]
	s_addc_u32 s49, s55, 0
	s_add_i32 vcc_hi, vcc_lo, 0x400
	s_mov_b32 m0, vcc_hi
	s_nop 0
	global_load_lds_dwordx4 v212, s[48:49]
	v_mfma_f32_16x16x32_bf16 v[192:195], v[192:195], v[152:155], v[168:171]
	v_add_u32_e32 v3, s80, v215
	ds_read_b128 v[230:233], v3
	s_add_u32 s48, s54, 0x100
	s_waitcnt lgkmcnt(2)
	v_mfma_f32_16x16x32_bf16 v[234:237], v[200:203], v[136:139], v[168:171]
	s_addc_u32 s49, s55, 0
	s_add_i32 s9, vcc_lo, 0x800
	s_mov_b32 m0, s9
	s_nop 0
	global_load_lds_dwordx4 v212, s[48:49]
	v_mfma_f32_16x16x32_bf16 v[200:203], v[200:203], v[152:155], v[168:171]
	ds_read_b128 v[238:241], v3 offset:8192
	s_add_u32 s48, s54, 0x180
	s_waitcnt lgkmcnt(2)
	v_mfma_f32_16x16x32_bf16 v[242:245], v[204:207], v[136:139], v[168:171]
	s_addc_u32 s49, s55, 0
	s_add_i32 s9, vcc_lo, 0xc00
	s_mov_b32 m0, s9
	s_nop 0
	global_load_lds_dwordx4 v212, s[48:49]
	v_mfma_f32_16x16x32_bf16 v[204:207], v[204:207], v[152:155], v[168:171]
	ds_read_b128 v[246:249], v3 offset:16384
	s_waitcnt lgkmcnt(2)
	v_mfma_f32_16x16x32_bf16 v[196:199], v[230:233], v[140:143], v[196:199]
	s_mov_b32 m0, s0
	s_nop 0
	global_load_lds_dwordx4 v213, s[70:71]
	v_mfma_f32_16x16x32_bf16 v[188:191], v[230:233], v[156:159], v[188:191]
	ds_read_b128 v[230:233], v3 offset:24576
	s_add_u32 s48, s70, 0x80
	s_waitcnt lgkmcnt(2)
	v_mfma_f32_16x16x32_bf16 v[192:195], v[238:241], v[156:159], v[192:195]
	s_addc_u32 s49, s71, 0
	s_add_i32 s9, s0, 0x400
	s_mov_b32 m0, s9
	s_nop 0
	global_load_lds_dwordx4 v213, s[48:49]
	v_mfma_f32_16x16x32_bf16 v[224:227], v[238:241], v[140:143], v[224:227]
	ds_read_b128 v[238:241], v2 offset:1024
	s_add_u32 s48, s70, 0x100
	s_waitcnt lgkmcnt(2)
	v_mfma_f32_16x16x32_bf16 v[234:237], v[246:249], v[140:143], v[234:237]
	s_addc_u32 s49, s71, 0
	s_add_i32 s9, s0, 0x800
	s_mov_b32 m0, s9
	s_nop 0
	global_load_lds_dwordx4 v213, s[48:49]
	v_mfma_f32_16x16x32_bf16 v[200:203], v[246:249], v[156:159], v[200:203]
	ds_read_b128 v[246:249], v2 offset:9216
	s_add_u32 s48, s70, 0x180
	s_waitcnt lgkmcnt(2)
	v_mfma_f32_16x16x32_bf16 v[204:207], v[230:233], v[156:159], v[204:207]
	s_addc_u32 s49, s71, 0
	s_addk_i32 s0, 0xc00
	s_mov_b32 m0, s0
	s_nop 0
	global_load_lds_dwordx4 v213, s[48:49]
	v_mfma_f32_16x16x32_bf16 v[242:245], v[230:233], v[140:143], v[242:245]
	ds_read_b128 v[230:233], v2 offset:17408
	s_waitcnt lgkmcnt(2)
	v_mfma_f32_16x16x32_bf16 v[196:199], v[238:241], v[144:147], v[196:199]
	v_mfma_f32_16x16x32_bf16 v[188:191], v[238:241], v[160:163], v[188:191]
	ds_read_b128 v[238:241], v2 offset:25600
	s_waitcnt lgkmcnt(2)
	v_mfma_f32_16x16x32_bf16 v[192:195], v[246:249], v[160:163], v[192:195]
	v_mfma_f32_16x16x32_bf16 v[224:227], v[246:249], v[144:147], v[224:227]
	ds_read_b128 v[246:249], v3 offset:1024
	s_waitcnt lgkmcnt(2)
	v_mfma_f32_16x16x32_bf16 v[234:237], v[230:233], v[144:147], v[234:237]
	v_mfma_f32_16x16x32_bf16 v[230:233], v[230:233], v[160:163], v[200:203]
	s_nop 2
	ds_read_b128 v[200:203], v3 offset:9216
	s_waitcnt lgkmcnt(2)
	v_mfma_f32_16x16x32_bf16 v[242:245], v[238:241], v[144:147], v[242:245]
	v_mfma_f32_16x16x32_bf16 v[238:241], v[238:241], v[160:163], v[204:207]
	s_waitcnt lgkmcnt(1)
	v_mfma_f32_16x16x32_bf16 v[250:253], v[246:249], v[148:151], v[196:199]
	s_nop 2
	ds_read_b128 v[196:199], v3 offset:17408
	v_mfma_f32_16x16x32_bf16 v[246:249], v[246:249], v[164:167], v[188:191]
	s_nop 2
	ds_read_b128 v[188:191], v3 offset:25600
	s_waitcnt lgkmcnt(2)
	v_mfma_f32_16x16x32_bf16 v[224:227], v[200:203], v[148:151], v[224:227]
	v_mfma_f32_16x16x32_bf16 v[204:207], v[200:203], v[164:167], v[192:195]
	s_waitcnt lgkmcnt(1)
	v_mfma_f32_16x16x32_bf16 v[200:203], v[196:199], v[148:151], v[234:237]
	v_mfma_f32_16x16x32_bf16 v[196:199], v[196:199], v[164:167], v[230:233]
	s_waitcnt lgkmcnt(0)
	v_mfma_f32_16x16x32_bf16 v[192:195], v[188:191], v[148:151], v[242:245]
	v_mfma_f32_16x16x32_bf16 v[188:191], v[188:191], v[164:167], v[238:241]
	v_add_u32_e32 v229, s50, v217
	s_nop 1
	v_add_u32_e32 v238, s50, v218
	ds_read_b64_tr_b16 v[230:231], v229 offset:32768
	ds_read_b64_tr_b16 v[232:233], v229 offset:40960
	ds_read_b64_tr_b16 v[234:235], v238 offset:32768
	ds_read_b64_tr_b16 v[236:237], v238 offset:40960
	v_mfma_f32_16x16x32_bf16 v[68:71], v[220:223], v[184:187], v[68:71]
	v_mov_b32_e32 v239, 0
	v_mov_b32_e32 v240, 0
	v_exp_f32_e32 v2, v250
	v_mfma_f32_16x16x32_bf16 v[132:135], v[220:223], v[180:183], v[132:135]
	v_add_u32_e32 v241, s50, v219
	ds_read_b64_tr_b16 v[220:221], v241 offset:32768
	ds_read_b64_tr_b16 v[222:223], v241 offset:40960
	s_waitcnt lgkmcnt(4)
; #define ATT_SB() __builtin_amdgcn_sched_barrier(0)
; #define A16_VLD(v, g) do { const LAS unsigned char* a_ = vbp[(g) & 3] + vso + ((g) >> 4) * 16384 + (((g) & 15) >> 2) * 1024; v[0] = vtr(a_); v[1] = vtr(a_ + 8192); } while (0)
; #define A16_GAP(i) do { A16_EL(i) = __builtin_amdgcn_exp2f(A16_EL(i)); \
;                 if ((i) > 0) { if ((((i) - 1) >> 2) & 1) s1 += A16_EL((i) - 1); else s0 += A16_EL((i) - 1); } asm volatile("" : "+v"(s0), "+v"(s1)); } while (0)
; __device__ __forceinline__ void attn_core16(f32x4 (&O)[16][2], float (&lq)[2], const bf16_t* Qw, int q_pitch, const bf16_t* Kh, const bf16_t* Vh, int kv_pitch,
;                                             int NT, int nt_act, int kch0, float negb, LAS unsigned char* ring, int wid) {
;     ...
; #pragma unroll
;             for (int g = 0; g < 32; ++g) {
;                 if (g + 2 < 32) A16_VLD(vv[(g + 2) % 3], g + 2);
;                 ATT_SB();
;                 O[g & 15][0] = __builtin_amdgcn_mfma_f32_16x16x32_bf16(A16_VF(vv[g % 3]), __builtin_bit_cast(bf16x8, pw[g >> 4][0]), O[g & 15][0], 0, 0, 0);
;                 O[g & 15][1] = __builtin_amdgcn_mfma_f32_16x16x32_bf16(A16_VF(vv[g % 3]), __builtin_bit_cast(bf16x8, pw[g >> 4][1]), O[g & 15][1], 0, 0, 0);
;                 A16_GAP(g);
;                 ATT_SB();
;             }
	v_mfma_f32_16x16x32_bf16 v[128:131], v[230:233], v[180:183], v[128:131]
	v_add_f32_e32 v239, v2, v239
	v_exp_f32_e32 v3, v251
	v_mfma_f32_16x16x32_bf16 v[64:67], v[230:233], v[184:187], v[64:67]
	ds_read_b64_tr_b16 v[230:231], v0 offset:33792
	ds_read_b64_tr_b16 v[232:233], v0 offset:41984
	s_waitcnt lgkmcnt(4)
	v_mfma_f32_16x16x32_bf16 v[60:63], v[234:237], v[184:187], v[60:63]
	v_add_f32_e32 v239, v3, v239
	v_exp_f32_e32 v242, v252
	v_mfma_f32_16x16x32_bf16 v[124:127], v[234:237], v[180:183], v[124:127]
	ds_read_b64_tr_b16 v[234:235], v229 offset:33792
	ds_read_b64_tr_b16 v[236:237], v229 offset:41984
	s_waitcnt lgkmcnt(4)
	v_mfma_f32_16x16x32_bf16 v[120:123], v[220:223], v[180:183], v[120:123]
	v_add_f32_e32 v239, v242, v239
	v_exp_f32_e32 v243, v253
	v_mfma_f32_16x16x32_bf16 v[56:59], v[220:223], v[184:187], v[56:59]
	ds_read_b64_tr_b16 v[220:221], v238 offset:33792
	ds_read_b64_tr_b16 v[222:223], v238 offset:41984
	s_waitcnt lgkmcnt(4)
	v_mfma_f32_16x16x32_bf16 v[52:55], v[230:233], v[184:187], v[52:55]
	v_add_f32_e32 v239, v243, v239
	v_exp_f32_e32 v244, v246
	v_mfma_f32_16x16x32_bf16 v[116:119], v[230:233], v[180:183], v[116:119]
	ds_read_b64_tr_b16 v[230:231], v241 offset:33792
	ds_read_b64_tr_b16 v[232:233], v241 offset:41984
	s_waitcnt lgkmcnt(4)
	v_mfma_f32_16x16x32_bf16 v[112:115], v[234:237], v[180:183], v[112:115]
	v_add_f32_e32 v240, v244, v240
	v_exp_f32_e32 v245, v247
	v_mfma_f32_16x16x32_bf16 v[48:51], v[234:237], v[184:187], v[48:51]
	ds_read_b64_tr_b16 v[234:235], v0 offset:34816
	ds_read_b64_tr_b16 v[236:237], v0 offset:43008
	s_waitcnt lgkmcnt(4)
	v_mfma_f32_16x16x32_bf16 v[44:47], v[220:223], v[184:187], v[44:47]
	v_add_f32_e32 v240, v245, v240
	v_exp_f32_e32 v246, v248
	v_mfma_f32_16x16x32_bf16 v[108:111], v[220:223], v[180:183], v[108:111]
	ds_read_b64_tr_b16 v[220:221], v229 offset:34816
	ds_read_b64_tr_b16 v[222:223], v229 offset:43008
	s_waitcnt lgkmcnt(4)
	v_mfma_f32_16x16x32_bf16 v[104:107], v[230:233], v[180:183], v[104:107]
	v_add_f32_e32 v240, v246, v240
	v_exp_f32_e32 v247, v249
	v_mfma_f32_16x16x32_bf16 v[40:43], v[230:233], v[184:187], v[40:43]
	ds_read_b64_tr_b16 v[230:231], v238 offset:34816
	ds_read_b64_tr_b16 v[232:233], v238 offset:43008
	s_waitcnt lgkmcnt(4)
	v_mfma_f32_16x16x32_bf16 v[36:39], v[234:237], v[184:187], v[36:39]
	v_add_f32_e32 v240, v247, v240
	v_exp_f32_e32 v248, v224
	v_mfma_f32_16x16x32_bf16 v[100:103], v[234:237], v[180:183], v[100:103]
	ds_read_b64_tr_b16 v[234:235], v241 offset:34816
	ds_read_b64_tr_b16 v[236:237], v241 offset:43008
	s_waitcnt lgkmcnt(4)
	v_mfma_f32_16x16x32_bf16 v[96:99], v[220:223], v[180:183], v[96:99]
	v_add_f32_e32 v224, v248, v239
	v_exp_f32_e32 v249, v225
	v_mfma_f32_16x16x32_bf16 v[32:35], v[220:223], v[184:187], v[32:35]
	ds_read_b64_tr_b16 v[220:221], v0 offset:35840
	ds_read_b64_tr_b16 v[222:223], v0 offset:44032
	s_waitcnt lgkmcnt(4)
	v_mfma_f32_16x16x32_bf16 v[28:31], v[230:233], v[184:187], v[28:31]
	v_add_f32_e32 v224, v249, v224
	v_exp_f32_e32 v239, v226
	v_mfma_f32_16x16x32_bf16 v[92:95], v[230:233], v[180:183], v[92:95]
	ds_read_b64_tr_b16 v[230:231], v229 offset:35840
	ds_read_b64_tr_b16 v[232:233], v229 offset:44032
	s_waitcnt lgkmcnt(4)
	v_mfma_f32_16x16x32_bf16 v[88:91], v[234:237], v[180:183], v[88:91]
	v_add_f32_e32 v251, v239, v224
	v_exp_f32_e32 v250, v227
	v_mfma_f32_16x16x32_bf16 v[24:27], v[234:237], v[184:187], v[24:27]
	ds_read_b64_tr_b16 v[224:225], v238 offset:35840
	ds_read_b64_tr_b16 v[226:227], v238 offset:44032
	s_waitcnt lgkmcnt(4)
	v_mfma_f32_16x16x32_bf16 v[20:23], v[220:223], v[184:187], v[20:23]
	v_exp_f32_e32 v234, v204
	v_add_f32_e32 v204, v250, v251
	v_mfma_f32_16x16x32_bf16 v[84:87], v[220:223], v[180:183], v[84:87]
	ds_read_b64_tr_b16 v[220:221], v241 offset:35840
	ds_read_b64_tr_b16 v[222:223], v241 offset:44032
	s_waitcnt lgkmcnt(4)
	v_mfma_f32_16x16x32_bf16 v[80:83], v[230:233], v[180:183], v[80:83]
	v_exp_f32_e32 v235, v205
	v_add_f32_e32 v205, v234, v240
	v_mfma_f32_16x16x32_bf16 v[16:19], v[230:233], v[184:187], v[16:19]
	ds_read_b64_tr_b16 v[230:231], v0 offset:49152
	ds_read_b64_tr_b16 v[232:233], v0 offset:57344
	s_waitcnt lgkmcnt(4)
	v_mfma_f32_16x16x32_bf16 v[12:15], v[224:227], v[184:187], v[12:15]
	v_add_f32_e32 v205, v235, v205
	v_exp_f32_e32 v236, v206
	v_mfma_f32_16x16x32_bf16 v[76:79], v[224:227], v[180:183], v[76:79]
	ds_read_b64_tr_b16 v[224:225], v229 offset:49152
	ds_read_b64_tr_b16 v[226:227], v229 offset:57344
	s_waitcnt lgkmcnt(4)
	v_mfma_f32_16x16x32_bf16 v[8:11], v[220:223], v[184:187], v[8:11]
	v_add_f32_e32 v184, v236, v205
	v_exp_f32_e32 v237, v207
	v_mfma_f32_16x16x32_bf16 v[72:75], v[220:223], v[180:183], v[72:75]
	ds_read_b64_tr_b16 v[180:181], v238 offset:49152
	ds_read_b64_tr_b16 v[182:183], v238 offset:57344
	s_waitcnt lgkmcnt(4)
	v_mfma_f32_16x16x32_bf16 v[68:71], v[230:233], v[176:179], v[68:71]
	v_add_f32_e32 v221, v237, v184
	v_exp_f32_e32 v220, v200
	v_mfma_f32_16x16x32_bf16 v[132:135], v[230:233], v[172:175], v[132:135]
	ds_read_b64_tr_b16 v[184:185], v241 offset:49152
	ds_read_b64_tr_b16 v[186:187], v241 offset:57344
	s_waitcnt lgkmcnt(4)
; #define ATT_SB() __builtin_amdgcn_sched_barrier(0)
; #define A16_PACK() do { _Pragma("unroll") for (int p_ = 0; p_ < 2; ++p_) _Pragma("unroll") for (int h_ = 0; h_ < 2; ++h_) \
;         pw[p_][h_] = (u32x4){pk2(S[2 * p_][h_][0], S[2 * p_][h_][1]), pk2(S[2 * p_][h_][2], S[2 * p_][h_][3]), pk2(S[2 * p_ + 1][h_][0], S[2 * p_ + 1][h_][1]), pk2(S[2 * p_ + 1][h_][2], S[2 * p_ + 1][h_][3])}; } while (0)
; #define A16_VLD(v, g) do { const LAS unsigned char* a_ = vbp[(g) & 3] + vso + ((g) >> 4) * 16384 + (((g) & 15) >> 2) * 1024; v[0] = vtr(a_); v[1] = vtr(a_ + 8192); } while (0)
; #define A16_GAP(i) do { A16_EL(i) = __builtin_amdgcn_exp2f(A16_EL(i)); \
;                 if ((i) > 0) { if ((((i) - 1) >> 2) & 1) s1 += A16_EL((i) - 1); else s0 += A16_EL((i) - 1); } asm volatile("" : "+v"(s0), "+v"(s1)); } while (0)
; __device__ __forceinline__ void attn_core16(f32x4 (&O)[16][2], float (&lq)[2], const bf16_t* Qw, int q_pitch, const bf16_t* Kh, const bf16_t* Vh, int kv_pitch,
;                                             int NT, int nt_act, int kch0, float negb, LAS unsigned char* ring, int wid) {
;     ...
; #pragma unroll
;             for (int g = 0; g < 32; ++g) {
;                 if (g + 2 < 32) A16_VLD(vv[(g + 2) % 3], g + 2);
;                 ATT_SB();
;                 O[g & 15][0] = __builtin_amdgcn_mfma_f32_16x16x32_bf16(A16_VF(vv[g % 3]), __builtin_bit_cast(bf16x8, pw[g >> 4][0]), O[g & 15][0], 0, 0, 0);
;                 O[g & 15][1] = __builtin_amdgcn_mfma_f32_16x16x32_bf16(A16_VF(vv[g % 3]), __builtin_bit_cast(bf16x8, pw[g >> 4][1]), O[g & 15][1], 0, 0, 0);
;                 A16_GAP(g);
;                 ATT_SB();
;             }
;     ...
;             l0 += more ? s0 : 0.f; l1 += more ? (s1 + A16_EL(31)) : 0.f;
;             A16_PACK();
	v_mfma_f32_16x16x32_bf16 v[128:131], v[224:227], v[172:175], v[128:131]
	v_add_f32_e32 v200, v220, v204
	v_exp_f32_e32 v222, v201
	v_mfma_f32_16x16x32_bf16 v[64:67], v[224:227], v[176:179], v[64:67]
	ds_read_b64_tr_b16 v[204:205], v0 offset:50176
	ds_read_b64_tr_b16 v[206:207], v0 offset:58368
	s_waitcnt lgkmcnt(4)
	v_mfma_f32_16x16x32_bf16 v[60:63], v[180:183], v[176:179], v[60:63]
	v_add_f32_e32 v200, v222, v200
	v_exp_f32_e32 v223, v202
	v_mfma_f32_16x16x32_bf16 v[124:127], v[180:183], v[172:175], v[124:127]
	ds_read_b64_tr_b16 v[180:181], v229 offset:50176
	ds_read_b64_tr_b16 v[182:183], v229 offset:58368
	s_waitcnt lgkmcnt(4)
	v_mfma_f32_16x16x32_bf16 v[120:123], v[184:187], v[172:175], v[120:123]
	v_add_f32_e32 v200, v223, v200
	v_exp_f32_e32 v224, v203
	v_mfma_f32_16x16x32_bf16 v[56:59], v[184:187], v[176:179], v[56:59]
	ds_read_b64_tr_b16 v[184:185], v238 offset:50176
	ds_read_b64_tr_b16 v[186:187], v238 offset:58368
	s_waitcnt lgkmcnt(4)
	v_mfma_f32_16x16x32_bf16 v[52:55], v[204:207], v[176:179], v[52:55]
	v_add_f32_e32 v226, v224, v200
	v_exp_f32_e32 v225, v196
	v_mfma_f32_16x16x32_bf16 v[116:119], v[204:207], v[172:175], v[116:119]
	ds_read_b64_tr_b16 v[200:201], v241 offset:50176
	ds_read_b64_tr_b16 v[202:203], v241 offset:58368
	s_waitcnt lgkmcnt(4)
	v_mfma_f32_16x16x32_bf16 v[112:115], v[180:183], v[172:175], v[112:115]
	v_add_f32_e32 v196, v225, v221
	v_exp_f32_e32 v204, v197
	v_mfma_f32_16x16x32_bf16 v[48:51], v[180:183], v[176:179], v[48:51]
	ds_read_b64_tr_b16 v[180:181], v0 offset:51200
	ds_read_b64_tr_b16 v[182:183], v0 offset:59392
	s_waitcnt lgkmcnt(4)
	v_mfma_f32_16x16x32_bf16 v[44:47], v[184:187], v[176:179], v[44:47]
	v_add_f32_e32 v196, v204, v196
	v_exp_f32_e32 v205, v198
	v_mfma_f32_16x16x32_bf16 v[108:111], v[184:187], v[172:175], v[108:111]
	ds_read_b64_tr_b16 v[184:185], v229 offset:51200
	ds_read_b64_tr_b16 v[186:187], v229 offset:59392
	s_waitcnt lgkmcnt(4)
	v_mfma_f32_16x16x32_bf16 v[104:107], v[200:203], v[172:175], v[104:107]
	v_add_f32_e32 v207, v205, v196
	v_exp_f32_e32 v206, v199
	v_mfma_f32_16x16x32_bf16 v[40:43], v[200:203], v[176:179], v[40:43]
	ds_read_b64_tr_b16 v[196:197], v238 offset:51200
	ds_read_b64_tr_b16 v[198:199], v238 offset:59392
	s_waitcnt lgkmcnt(4)
	v_mfma_f32_16x16x32_bf16 v[36:39], v[180:183], v[176:179], v[36:39]
	v_add_f32_e32 v200, v206, v207
	v_exp_f32_e32 v192, v192
	v_mfma_f32_16x16x32_bf16 v[100:103], v[180:183], v[172:175], v[100:103]
	ds_read_b64_tr_b16 v[180:181], v241 offset:51200
	ds_read_b64_tr_b16 v[182:183], v241 offset:59392
	s_waitcnt lgkmcnt(4)
	v_mfma_f32_16x16x32_bf16 v[96:99], v[184:187], v[172:175], v[96:99]
	v_add_f32_e32 v201, v192, v226
	v_exp_f32_e32 v193, v193
	v_mfma_f32_16x16x32_bf16 v[32:35], v[184:187], v[176:179], v[32:35]
	ds_read_b64_tr_b16 v[184:185], v0 offset:52224
	ds_read_b64_tr_b16 v[186:187], v0 offset:60416
	s_waitcnt lgkmcnt(4)
	v_mfma_f32_16x16x32_bf16 v[28:31], v[196:199], v[176:179], v[28:31]
	v_exp_f32_e32 v0, v194
	v_add_f32_e32 v194, v193, v201
	v_mfma_f32_16x16x32_bf16 v[92:95], v[196:199], v[172:175], v[92:95]
	ds_read_b64_tr_b16 v[196:197], v229 offset:52224
	ds_read_b64_tr_b16 v[198:199], v229 offset:60416
	s_waitcnt lgkmcnt(4)
	v_mfma_f32_16x16x32_bf16 v[88:91], v[180:183], v[172:175], v[88:91]
	v_add_f32_e32 v194, v0, v194
	v_exp_f32_e32 v195, v195
	v_mfma_f32_16x16x32_bf16 v[24:27], v[180:183], v[176:179], v[24:27]
	ds_read_b64_tr_b16 v[180:181], v238 offset:52224
	ds_read_b64_tr_b16 v[182:183], v238 offset:60416
	s_waitcnt lgkmcnt(4)
	v_mfma_f32_16x16x32_bf16 v[20:23], v[184:187], v[176:179], v[20:23]
	v_exp_f32_e32 v201, v188
	v_add_f32_e32 v188, v195, v194
	v_mfma_f32_16x16x32_bf16 v[84:87], v[184:187], v[172:175], v[84:87]
	ds_read_b64_tr_b16 v[184:185], v241 offset:52224
	ds_read_b64_tr_b16 v[186:187], v241 offset:60416
	s_waitcnt lgkmcnt(4)
	v_mfma_f32_16x16x32_bf16 v[80:83], v[196:199], v[172:175], v[80:83]
	v_exp_f32_e32 v194, v189
	v_add_f32_e32 v189, v201, v200
	v_mfma_f32_16x16x32_bf16 v[16:19], v[196:199], v[176:179], v[16:19]
	s_waitcnt lgkmcnt(2)
	v_mfma_f32_16x16x32_bf16 v[12:15], v[180:183], v[176:179], v[12:15]
	v_add_f32_e32 v189, v194, v189
	v_exp_f32_e32 v190, v190
	v_mfma_f32_16x16x32_bf16 v[76:79], v[180:183], v[172:175], v[76:79]
	v_cvt_pk_bf16_f32 v180, v244, v245
	v_cvt_pk_bf16_f32 v181, v246, v247
	v_cvt_pk_bf16_f32 v182, v234, v235
	v_cvt_pk_bf16_f32 v183, v236, v237
	s_waitcnt lgkmcnt(0)
	v_mfma_f32_16x16x32_bf16 v[8:11], v[184:187], v[176:179], v[8:11]
	v_add_f32_e32 v176, v190, v189
	v_exp_f32_e32 v191, v191
	v_mfma_f32_16x16x32_bf16 v[72:75], v[184:187], v[172:175], v[72:75]
	s_cmp_lt_u32 s20, s73
	v_add_f32_e32 v172, v191, v176
	s_cselect_b64 vcc, -1, 0
	v_cndmask_b32_e32 v189, 0, v188, vcc
	v_cndmask_b32_e32 v188, 0, v172, vcc
	v_cvt_pk_bf16_f32 v184, v2, v3
	v_cvt_pk_bf16_f32 v185, v242, v243
	v_cvt_pk_bf16_f32 v186, v248, v249
	v_cvt_pk_bf16_f32 v187, v239, v250
	v_cvt_pk_bf16_f32 v176, v220, v222
	v_cvt_pk_bf16_f32 v177, v223, v224
	v_cvt_pk_bf16_f32 v178, v192, v193
	v_cvt_pk_bf16_f32 v179, v0, v195
	v_cvt_pk_bf16_f32 v172, v225, v204
	v_cvt_pk_bf16_f32 v173, v205, v206
	v_cvt_pk_bf16_f32 v174, v201, v194
	v_cvt_pk_bf16_f32 v175, v190, v191
	v_pk_add_f32 v[208:209], v[208:209], v[188:189]
